# diff-attn QK segments: only 6 of the 16 exps issued before the first MFMA, the rest spread into the MFMA gaps
# speedup vs baseline: 1.0096x; 1.0096x over previous
; __device__ __forceinline__ void finishSM(f32x16& p0, f32x16& p1, float alpha, float& l_reg, bf16x8& pa0, bf16x8& pa1, bf16x8& pa2, bf16x8& pa3) {
;     for (int r = 0; r < 16; ++r) p1[r] = __builtin_amdgcn_exp2f(p1[r]);
;     float ps = 0; for (int r = 0; r < 16; ++r) ps += p0[r]; for (int r = 0; r < 16; ++r) ps += p1[r];
;     { auto rr = __builtin_amdgcn_permlane32_swap(__float_as_uint(ps), __float_as_uint(ps), false, false);
;       ps = __uint_as_float(rr[0]) + __uint_as_float(rr[1]); }
;     l_reg = l_reg * alpha + ps;
;     ...
;     PK4(p0, 0, pa0); PK4(p0, 8, pa1); PK4(p1, 0, pa2); PK4(p1, 8, pa3);
;     ...
; }
; template <int KB, bool SK>
; __device__ __forceinline__ void qkt(f32x16& p0, f32x16& p1, const char* K_lds, int r32, int hi, const bf16x8* qr, bool act) {
;     if (SK && !act) { const float NEG = -__builtin_inff();
; #pragma unroll
;         for (int r = 0; r < 16; ++r) { p0[r] = NEG; p1[r] = NEG; } return; }
;     p0 = f32x16{}; p1 = f32x16{};
;     const char* kb[4];
; #pragma unroll
;     for (int dd = 0; dd < 4; ++dd) kb[dd] = K_lds + KB * SHM_K + KSWZ(r32, (dd * 16 + hi * 8) * 2);
; #pragma unroll
;     for (int d0 = 0; d0 < 8; ++d0) { const char* a = kb[d0 & 3] + (d0 >> 2) * 128;
;         bf16x8 b0 = *reinterpret_cast<const bf16x8*>(a);
;         bf16x8 b1 = *reinterpret_cast<const bf16x8*>(a + 32 * 256);
;         const bf16x8 qf = qr[d0];
;         p0 = __builtin_amdgcn_mfma_f32_32x32x16_bf16(b0, qf, p0, 0, 0, 0);
;         p1 = __builtin_amdgcn_mfma_f32_32x32x16_bf16(b1, qf, p1, 0, 0, 0); }
; }
.Lattn_prio_skip:
.LBB0_1129:
	ds_read_b128 v[180:183], v211 offset:49152
	ds_read_b128 v[184:187], v211 offset:57344
	ds_read_b128 v[188:191], v212 offset:49152
	ds_read_b128 v[228:231], v212 offset:57344
	ds_read_b128 v[232:235], v213 offset:49152
	ds_read_b128 v[236:239], v213 offset:57344
	ds_read_b128 v[240:243], v214 offset:49152
	ds_read_b128 v[244:247], v214 offset:57344
	v_exp_f32_e32 v126, v126
	v_exp_f32_e32 v127, v127
	v_exp_f32_e32 v124, v124
	v_exp_f32_e32 v125, v125
	v_exp_f32_e32 v120, v120
	v_exp_f32_e32 v121, v121
	s_add_i32 s4, s26, 0xffffff81
	s_sub_i32 s5, s26, 64
	s_waitcnt lgkmcnt(7)
	v_mfma_f32_32x32x16_bf16 v[86:101], v[180:183], v[158:161], 0
	ds_read_b128 v[180:183], v211 offset:49280
	v_exp_f32_e32 v116, v116
	v_exp_f32_e32 v117, v117
	v_exp_f32_e32 v114, v114
	v_exp_f32_e32 v115, v115
	v_exp_f32_e32 v128, v128
	s_waitcnt lgkmcnt(7)
	v_mfma_f32_32x32x16_bf16 v[70:85], v[184:187], v[158:161], 0
	ds_read_b128 v[184:187], v211 offset:57472
	v_exp_f32_e32 v129, v129
	v_exp_f32_e32 v122, v122
	v_exp_f32_e32 v123, v123
	v_exp_f32_e32 v118, v118
	v_exp_f32_e32 v119, v119
	s_waitcnt lgkmcnt(7)
	v_mfma_f32_32x32x16_bf16 v[86:101], v[188:191], v[154:157], v[86:101]
	ds_read_b128 v[188:191], v212 offset:49280
	v_add_f32_e32 v179, 0, v170
	v_add_f32_e32 v179, v171, v179
	v_add_f32_e32 v179, v172, v179
	v_add_f32_e32 v179, v173, v179
	v_add_f32_e32 v179, v174, v179
	s_waitcnt lgkmcnt(7)
	v_mfma_f32_32x32x16_bf16 v[70:85], v[228:231], v[154:157], v[70:85]
	ds_read_b128 v[228:231], v212 offset:57472
	v_add_f32_e32 v179, v176, v179
	v_add_f32_e32 v179, v175, v179
	v_add_f32_e32 v179, v177, v179
	v_add_f32_e32 v179, v162, v179
	v_add_f32_e32 v179, v163, v179
	s_waitcnt lgkmcnt(7)
	v_mfma_f32_32x32x16_bf16 v[86:101], v[232:235], v[150:153], v[86:101]
	ds_read_b128 v[232:235], v213 offset:49280
	v_add_f32_e32 v110, v164, v179
	v_add_f32_e32 v110, v166, v110
	v_add_f32_e32 v110, v165, v110
	v_add_f32_e32 v110, v167, v110
	s_waitcnt lgkmcnt(7)
	v_mfma_f32_32x32x16_bf16 v[70:85], v[236:239], v[150:153], v[70:85]
	ds_read_b128 v[236:239], v213 offset:57472
	v_add_f32_e32 v110, v168, v110
	v_add_f32_e32 v110, v169, v110
	v_add_f32_e32 v110, v126, v110
	v_add_f32_e32 v102, v127, v110
	s_waitcnt lgkmcnt(7)
	v_mfma_f32_32x32x16_bf16 v[86:101], v[240:243], v[134:137], v[86:101]
	ds_read_b128 v[240:243], v214 offset:49280
	v_add_f32_e32 v102, v124, v102
	v_add_f32_e32 v102, v125, v102
	v_add_f32_e32 v102, v120, v102
	v_add_f32_e32 v102, v121, v102
	s_waitcnt lgkmcnt(7)
	v_mfma_f32_32x32x16_bf16 v[70:85], v[244:247], v[134:137], v[70:85]
	ds_read_b128 v[244:247], v214 offset:57472
	v_add_f32_e32 v102, v116, v102
	v_add_f32_e32 v102, v117, v102
	v_add_f32_e32 v102, v114, v102
	v_add_f32_e32 v102, v115, v102
	s_waitcnt lgkmcnt(7)
	v_mfma_f32_32x32x16_bf16 v[86:101], v[180:183], v[138:141], v[86:101]
	v_add_f32_e32 v102, v128, v102
	v_add_f32_e32 v102, v129, v102
	v_add_f32_e32 v102, v122, v102
	v_add_f32_e32 v102, v123, v102
	s_waitcnt lgkmcnt(6)
	v_mfma_f32_32x32x16_bf16 v[70:85], v[184:187], v[138:141], v[70:85]
	v_add_f32_e32 v102, v118, v102
	v_add_f32_e32 v223, v119, v102
	v_mov_b32_e32 v224, v223
	s_nop 1
	v_permlane32_swap_b32_e32 v223, v224
	s_waitcnt lgkmcnt(5)
	v_mfma_f32_32x32x16_bf16 v[86:101], v[188:191], v[142:145], v[86:101]
	v_cvt_pk_bf16_f32 v102, v170, v171
	v_cvt_pk_bf16_f32 v103, v172, v173
	v_cvt_pk_bf16_f32 v104, v174, v176
	v_cvt_pk_bf16_f32 v105, v175, v177
	s_waitcnt lgkmcnt(4)
	v_mfma_f32_32x32x16_bf16 v[70:85], v[228:231], v[142:145], v[70:85]
	v_cvt_pk_bf16_f32 v66, v162, v163
	v_cvt_pk_bf16_f32 v67, v164, v166
	v_cvt_pk_bf16_f32 v68, v165, v167
	v_cvt_pk_bf16_f32 v69, v168, v169
	s_waitcnt lgkmcnt(3)
	v_mfma_f32_32x32x16_bf16 v[86:101], v[232:235], v[146:149], v[86:101]
	v_cvt_pk_bf16_f32 v106, v126, v127
	v_cvt_pk_bf16_f32 v107, v124, v125
	v_cvt_pk_bf16_f32 v108, v120, v121
	v_cvt_pk_bf16_f32 v109, v116, v117
	s_waitcnt lgkmcnt(2)
	v_mfma_f32_32x32x16_bf16 v[70:85], v[236:239], v[146:149], v[70:85]
	v_cvt_pk_bf16_f32 v110, v114, v115
	v_cvt_pk_bf16_f32 v111, v128, v129
	v_cvt_pk_bf16_f32 v112, v122, v123
	v_cvt_pk_bf16_f32 v113, v118, v119
	s_waitcnt lgkmcnt(1)
	v_mfma_f32_32x32x16_bf16 v[86:101], v[240:243], v[130:133], v[86:101]
	s_nop 1
	v_permlane32_swap_b32_e32 v102, v104
	v_permlane32_swap_b32_e32 v103, v105
	v_permlane32_swap_b32_e32 v66, v68
	v_permlane32_swap_b32_e32 v67, v69
	s_waitcnt lgkmcnt(0)
	v_mfma_f32_32x32x16_bf16 v[70:85], v[244:247], v[130:133], v[70:85]
	v_permlane32_swap_b32_e32 v106, v108
	v_permlane32_swap_b32_e32 v107, v109
	v_permlane32_swap_b32_e32 v110, v112
	v_permlane32_swap_b32_e32 v111, v113
	v_add_u32_e32 v114, 0x2000, v255
	global_load_dwordx4 v[162:165], v255, s[42:43]
	global_load_dwordx4 v[166:169], v114, s[42:43]
	global_load_dwordx4 v[170:173], v255, s[22:23]
	global_load_dwordx4 v[174:177], v114, s[22:23]
	s_cmp_le_i32 s5, s13
	s_cselect_b64 s[52:53], -1, 0
	s_cmp_gt_i32 s4, s15
	s_cselect_b64 s[4:5], -1, 0
	s_and_b64 s[4:5], s[52:53], s[4:5]
	s_and_b64 vcc, exec, s[4:5]
	ds_read_b64_tr_b16 v[114:115], v202 offset:0x0
	ds_read_b64_tr_b16 v[116:117], v202 offset:0x800
	ds_read_b64_tr_b16 v[118:119], v202 offset:0x1000
	ds_read_b64_tr_b16 v[120:121], v202 offset:0x1800
	ds_read_b64_tr_b16 v[122:123], v202 offset:0x2000
	ds_read_b64_tr_b16 v[124:125], v202 offset:0x2800
	ds_read_b64_tr_b16 v[126:127], v202 offset:0x3000
	ds_read_b64_tr_b16 v[128:129], v202 offset:0x3800
	ds_read_b64_tr_b16 v[182:183], v202 offset:0x200
	ds_read_b64_tr_b16 v[184:185], v202 offset:0xa00
	ds_read_b64_tr_b16 v[186:187], v202 offset:0x1200
	ds_read_b64_tr_b16 v[188:189], v202 offset:0x1a00
	ds_read_b64_tr_b16 v[190:191], v202 offset:0x2200
	ds_read_b64_tr_b16 v[192:193], v202 offset:0x2a00
	s_cbranch_vccnz .Lh1_nomask
; __device__ __forceinline__ void mask_tile(f32x16& p0, f32x16& p1, int dq, unsigned W) {
;     const float NEG = -__builtin_inff();
; #pragma unroll
;     for (int r = 0; r < 16; ++r) {
;         const int c = (r & 3) + 8 * (r >> 2);
;         if ((unsigned)(dq - c) >= W) p0[r] = NEG;
;         if ((unsigned)(dq - c - 32) >= W) p1[r] = NEG;
;     }
; }
	v_add_u32_e32 v226, s80, v222
	v_subrev_u32_e32 v240, 64, v226
	v_cmp_gt_u32_e32 vcc, s85, v240
	v_add_u32_e32 v240, 0xffffffa0, v226
	s_nop 0
	v_cndmask_b32_e32 v86, v215, v86, vcc
	v_cmp_gt_u32_e32 vcc, s85, v240
	v_add_u32_e32 v240, 0xffffffbf, v226
	s_nop 0
	v_cndmask_b32_e32 v70, v215, v70, vcc
	v_cmp_gt_u32_e32 vcc, s85, v240
	v_add_u32_e32 v240, 0xffffff9f, v226
	s_nop 0
	v_cndmask_b32_e32 v87, v215, v87, vcc
	v_cmp_gt_u32_e32 vcc, s85, v240
	v_add_u32_e32 v240, 0xffffffbe, v226
	s_nop 0
	v_cndmask_b32_e32 v71, v215, v71, vcc
	v_cmp_gt_u32_e32 vcc, s85, v240
	v_add_u32_e32 v240, 0xffffff9e, v226
	s_nop 0
	v_cndmask_b32_e32 v88, v215, v88, vcc
	v_cmp_gt_u32_e32 vcc, s85, v240
	v_add_u32_e32 v240, 0xffffffbd, v226
	s_nop 0
	v_cndmask_b32_e32 v72, v215, v72, vcc
	v_cmp_gt_u32_e32 vcc, s85, v240
	v_add_u32_e32 v240, 0xffffff9d, v226
	s_nop 0
	v_cndmask_b32_e32 v89, v215, v89, vcc
	v_cmp_gt_u32_e32 vcc, s85, v240
	v_add_u32_e32 v240, 0xffffffb8, v226
	s_nop 0
	v_cndmask_b32_e32 v73, v215, v73, vcc
	v_cmp_gt_u32_e32 vcc, s85, v240
	v_add_u32_e32 v240, 0xffffff98, v226
	s_nop 0
	v_cndmask_b32_e32 v90, v215, v90, vcc
	v_cmp_gt_u32_e32 vcc, s85, v240
	v_add_u32_e32 v240, 0xffffffb7, v226
	s_nop 0
	v_cndmask_b32_e32 v74, v215, v74, vcc
	v_cmp_gt_u32_e32 vcc, s85, v240
	v_add_u32_e32 v240, 0xffffff97, v226
	s_nop 0
	v_cndmask_b32_e32 v91, v215, v91, vcc
	v_cmp_gt_u32_e32 vcc, s85, v240
	v_add_u32_e32 v240, 0xffffffb6, v226
	s_nop 0
	v_cndmask_b32_e32 v75, v215, v75, vcc
	v_cmp_gt_u32_e32 vcc, s85, v240
	v_add_u32_e32 v240, 0xffffff96, v226
	s_nop 0
	v_cndmask_b32_e32 v92, v215, v92, vcc
	v_cmp_gt_u32_e32 vcc, s85, v240
	v_add_u32_e32 v240, 0xffffffb5, v226
	s_nop 0
	v_cndmask_b32_e32 v76, v215, v76, vcc
	v_cmp_gt_u32_e32 vcc, s85, v240
	v_add_u32_e32 v240, 0xffffff95, v226
	s_nop 0
	v_cndmask_b32_e32 v93, v215, v93, vcc
	v_cmp_gt_u32_e32 vcc, s85, v240
	v_add_u32_e32 v240, 0xffffffb0, v226
	s_nop 0
	v_cndmask_b32_e32 v77, v215, v77, vcc
	v_cmp_gt_u32_e32 vcc, s85, v240
	v_add_u32_e32 v240, 0xffffff90, v226
	s_nop 0
	v_cndmask_b32_e32 v94, v215, v94, vcc
	v_cmp_gt_u32_e32 vcc, s85, v240
	v_add_u32_e32 v240, 0xffffffaf, v226
	s_nop 0
	v_cndmask_b32_e32 v78, v215, v78, vcc
	v_cmp_gt_u32_e32 vcc, s85, v240
	v_add_u32_e32 v240, 0xffffff8f, v226
	s_nop 0
	v_cndmask_b32_e32 v95, v215, v95, vcc
	v_cmp_gt_u32_e32 vcc, s85, v240
	v_add_u32_e32 v240, 0xffffffae, v226
	s_nop 0
	v_cndmask_b32_e32 v79, v215, v79, vcc
	v_cmp_gt_u32_e32 vcc, s85, v240
	v_add_u32_e32 v240, 0xffffff8e, v226
	s_nop 0
	v_cndmask_b32_e32 v96, v215, v96, vcc
	v_cmp_gt_u32_e32 vcc, s85, v240
	v_add_u32_e32 v240, 0xffffffad, v226
	s_nop 0
	v_cndmask_b32_e32 v80, v215, v80, vcc
	v_cmp_gt_u32_e32 vcc, s85, v240
	v_add_u32_e32 v240, 0xffffff8d, v226
	s_nop 0
	v_cndmask_b32_e32 v97, v215, v97, vcc
	v_cmp_gt_u32_e32 vcc, s85, v240
	v_add_u32_e32 v240, 0xffffffa8, v226
	s_nop 0
	v_cndmask_b32_e32 v81, v215, v81, vcc
	v_cmp_gt_u32_e32 vcc, s85, v240
	v_add_u32_e32 v240, 0xffffff88, v226
	s_nop 0
	v_cndmask_b32_e32 v98, v215, v98, vcc
	v_cmp_gt_u32_e32 vcc, s85, v240
	v_add_u32_e32 v240, 0xffffffa7, v226
	s_nop 0
	v_cndmask_b32_e32 v82, v215, v82, vcc
	v_cmp_gt_u32_e32 vcc, s85, v240
	v_add_u32_e32 v240, 0xffffff87, v226
	s_nop 0
	v_cndmask_b32_e32 v99, v215, v99, vcc
	v_cmp_gt_u32_e32 vcc, s85, v240
	v_add_u32_e32 v240, 0xffffffa6, v226
	s_nop 0
	v_cndmask_b32_e32 v83, v215, v83, vcc
	v_cmp_gt_u32_e32 vcc, s85, v240
	v_add_u32_e32 v240, 0xffffff86, v226
	s_nop 0
	v_cndmask_b32_e32 v100, v215, v100, vcc
	v_cmp_gt_u32_e32 vcc, s85, v240
	v_add_u32_e32 v240, 0xffffffa5, v226
	s_nop 0
	v_cndmask_b32_e32 v84, v215, v84, vcc
	v_cmp_gt_u32_e32 vcc, s85, v240
	v_add_u32_e32 v240, 0xffffff85, v226
	s_nop 0
	v_cndmask_b32_e32 v101, v215, v101, vcc
	v_cmp_gt_u32_e32 vcc, s85, v240
	s_nop 1
	v_cndmask_b32_e32 v85, v215, v85, vcc

; __device__ __forceinline__ void finishSM(f32x16& p0, f32x16& p1, float alpha, float& l_reg, bf16x8& pa0, bf16x8& pa1, bf16x8& pa2, bf16x8& pa3) {
;     for (int r = 0; r < 16; ++r) p1[r] = __builtin_amdgcn_exp2f(p1[r]);
;     float ps = 0; for (int r = 0; r < 16; ++r) ps += p0[r]; for (int r = 0; r < 16; ++r) ps += p1[r];
;     { auto rr = __builtin_amdgcn_permlane32_swap(__float_as_uint(ps), __float_as_uint(ps), false, false);
;       ps = __uint_as_float(rr[0]) + __uint_as_float(rr[1]); }
;     l_reg = l_reg * alpha + ps;
;     ...
;     PK4(p0, 0, pa0); PK4(p0, 8, pa1); PK4(p1, 0, pa2); PK4(p1, 8, pa3);
;     ...
; }
; template <int KB, bool SK>
; __device__ __forceinline__ void qkt(f32x16& p0, f32x16& p1, const char* K_lds, int r32, int hi, const bf16x8* qr, bool act) {
;     if (SK && !act) { const float NEG = -__builtin_inff();
; #pragma unroll
;         for (int r = 0; r < 16; ++r) { p0[r] = NEG; p1[r] = NEG; } return; }
;     p0 = f32x16{}; p1 = f32x16{};
;     const char* kb[4];
; #pragma unroll
;     for (int dd = 0; dd < 4; ++dd) kb[dd] = K_lds + KB * SHM_K + KSWZ(r32, (dd * 16 + hi * 8) * 2);
; #pragma unroll
;     for (int d0 = 0; d0 < 8; ++d0) { const char* a = kb[d0 & 3] + (d0 >> 2) * 128;
;         bf16x8 b0 = *reinterpret_cast<const bf16x8*>(a);
;         bf16x8 b1 = *reinterpret_cast<const bf16x8*>(a + 32 * 256);
;         const bf16x8 qf = qr[d0];
;         p0 = __builtin_amdgcn_mfma_f32_32x32x16_bf16(b0, qf, p0, 0, 0, 0);
;         p1 = __builtin_amdgcn_mfma_f32_32x32x16_bf16(b1, qf, p1, 0, 0, 0); }
; }
.Lh1_noresc:
	v_exp_f32_e32 v66, v228
	v_exp_f32_e32 v67, v229
	v_exp_f32_e32 v68, v230
	v_exp_f32_e32 v69, v231
	v_exp_f32_e32 v70, v232
	v_exp_f32_e32 v71, v233
	v_exp_f32_e32 v72, v234
	v_exp_f32_e32 v73, v235
	v_exp_f32_e32 v74, v236
	v_exp_f32_e32 v75, v237
	v_exp_f32_e32 v76, v238
	v_exp_f32_e32 v77, v239
	v_exp_f32_e32 v78, v98
	v_exp_f32_e32 v79, v99
	v_exp_f32_e32 v80, v100
	v_exp_f32_e32 v81, v101
	s_waitcnt lgkmcnt(0)
	s_barrier
	ds_read_b128 v[162:165], v211 offset:32768
	ds_read_b128 v[166:169], v211 offset:40960
	ds_read_b128 v[170:173], v212 offset:32768
	ds_read_b128 v[174:177], v212 offset:40960
	ds_read_b128 v[230:233], v213 offset:32768
	ds_read_b128 v[234:237], v213 offset:40960
	ds_read_b128 v[238:241], v214 offset:32768
	ds_read_b128 v[242:245], v214 offset:40960
	v_exp_f32_e32 v82, v86
	v_exp_f32_e32 v83, v95
	v_exp_f32_e32 v84, v96
	v_exp_f32_e32 v85, v97
	v_exp_f32_e32 v86, v179
	v_exp_f32_e32 v87, v87
	s_waitcnt lgkmcnt(7)
	v_mfma_f32_32x32x16_bf16 v[114:129], v[162:165], v[158:161], 0
	ds_read_b128 v[162:165], v211 offset:32896
	v_exp_f32_e32 v88, v88
	v_exp_f32_e32 v89, v89
	v_exp_f32_e32 v90, v90
	v_exp_f32_e32 v91, v91
	v_exp_f32_e32 v92, v92
	s_waitcnt lgkmcnt(7)
	v_mfma_f32_32x32x16_bf16 v[98:113], v[166:169], v[158:161], 0
	ds_read_b128 v[166:169], v211 offset:41088
	v_exp_f32_e32 v93, v93
	v_exp_f32_e32 v94, v94
	v_exp_f32_e32 v95, v180
	v_exp_f32_e32 v96, v181
	v_exp_f32_e32 v97, v178
	s_waitcnt lgkmcnt(7)
	v_mfma_f32_32x32x16_bf16 v[114:129], v[170:173], v[154:157], v[114:129]
	ds_read_b128 v[170:173], v212 offset:32896
	v_add_f32_e32 v178, 0, v66
	v_add_f32_e32 v178, v67, v178
	v_add_f32_e32 v178, v68, v178
	v_add_f32_e32 v178, v69, v178
	v_add_f32_e32 v178, v70, v178
	s_waitcnt lgkmcnt(7)
	v_mfma_f32_32x32x16_bf16 v[98:113], v[174:177], v[154:157], v[98:113]
	ds_read_b128 v[174:177], v212 offset:41088
	v_add_f32_e32 v178, v71, v178
	v_add_f32_e32 v178, v72, v178
	v_add_f32_e32 v178, v73, v178
	v_add_f32_e32 v178, v74, v178
	v_add_f32_e32 v178, v75, v178
	s_waitcnt lgkmcnt(7)
	v_mfma_f32_32x32x16_bf16 v[114:129], v[230:233], v[150:153], v[114:129]
	ds_read_b128 v[230:233], v213 offset:32896
	v_add_f32_e32 v178, v76, v178
	v_add_f32_e32 v178, v77, v178
	v_add_f32_e32 v178, v78, v178
	v_add_f32_e32 v178, v79, v178
	s_waitcnt lgkmcnt(7)
	v_mfma_f32_32x32x16_bf16 v[98:113], v[234:237], v[150:153], v[98:113]
	ds_read_b128 v[234:237], v213 offset:41088
	v_add_f32_e32 v178, v80, v178
	v_add_f32_e32 v178, v81, v178
	v_add_f32_e32 v178, v82, v178
	v_add_f32_e32 v178, v83, v178
	s_waitcnt lgkmcnt(7)
	v_mfma_f32_32x32x16_bf16 v[114:129], v[238:241], v[134:137], v[114:129]
	ds_read_b128 v[238:241], v214 offset:32896
	v_add_f32_e32 v178, v84, v178
	v_add_f32_e32 v178, v85, v178
	v_add_f32_e32 v178, v86, v178
	v_add_f32_e32 v178, v87, v178
	s_waitcnt lgkmcnt(7)
	v_mfma_f32_32x32x16_bf16 v[98:113], v[242:245], v[134:137], v[98:113]
	ds_read_b128 v[242:245], v214 offset:41088
	v_add_f32_e32 v178, v88, v178
	v_add_f32_e32 v178, v89, v178
	v_add_f32_e32 v178, v90, v178
	v_add_f32_e32 v178, v91, v178
	s_waitcnt lgkmcnt(7)
	v_mfma_f32_32x32x16_bf16 v[114:129], v[162:165], v[138:141], v[114:129]
	v_add_f32_e32 v178, v92, v178
	v_add_f32_e32 v178, v93, v178
	v_add_f32_e32 v178, v94, v178
	v_add_f32_e32 v178, v95, v178
	s_waitcnt lgkmcnt(6)
	v_mfma_f32_32x32x16_bf16 v[98:113], v[166:169], v[138:141], v[98:113]
	v_add_f32_e32 v178, v96, v178
	v_add_f32_e32 v228, v97, v178
	v_mov_b32_e32 v229, v228
	s_nop 1
	v_permlane32_swap_b32_e32 v228, v229
	s_waitcnt lgkmcnt(5)
	v_mfma_f32_32x32x16_bf16 v[114:129], v[170:173], v[142:145], v[114:129]
	v_cvt_pk_bf16_f32 v178, v66, v67
	v_cvt_pk_bf16_f32 v179, v68, v69
	v_cvt_pk_bf16_f32 v180, v70, v71
	v_cvt_pk_bf16_f32 v181, v72, v73
	s_waitcnt lgkmcnt(4)
	v_mfma_f32_32x32x16_bf16 v[98:113], v[174:177], v[142:145], v[98:113]
	v_cvt_pk_bf16_f32 v182, v74, v75
	v_cvt_pk_bf16_f32 v183, v76, v77
	v_cvt_pk_bf16_f32 v184, v78, v79
	v_cvt_pk_bf16_f32 v185, v80, v81
	s_waitcnt lgkmcnt(3)
	v_mfma_f32_32x32x16_bf16 v[114:129], v[230:233], v[146:149], v[114:129]
	v_cvt_pk_bf16_f32 v186, v82, v83
	v_cvt_pk_bf16_f32 v187, v84, v85
	v_cvt_pk_bf16_f32 v188, v86, v87
	v_cvt_pk_bf16_f32 v189, v88, v89
	s_waitcnt lgkmcnt(2)
	v_mfma_f32_32x32x16_bf16 v[98:113], v[234:237], v[146:149], v[98:113]
	v_cvt_pk_bf16_f32 v190, v90, v91
	v_cvt_pk_bf16_f32 v191, v92, v93
	v_cvt_pk_bf16_f32 v192, v94, v95
	v_cvt_pk_bf16_f32 v193, v96, v97
	s_waitcnt lgkmcnt(1)
	v_mfma_f32_32x32x16_bf16 v[114:129], v[238:241], v[130:133], v[114:129]
	s_nop 1
	v_permlane32_swap_b32_e32 v178, v180
	v_permlane32_swap_b32_e32 v179, v181
	v_permlane32_swap_b32_e32 v182, v184
	v_permlane32_swap_b32_e32 v183, v185
	s_waitcnt lgkmcnt(0)
	v_mfma_f32_32x32x16_bf16 v[98:113], v[242:245], v[130:133], v[98:113]
	v_permlane32_swap_b32_e32 v186, v188
	v_permlane32_swap_b32_e32 v187, v189
	v_permlane32_swap_b32_e32 v190, v192
	v_permlane32_swap_b32_e32 v191, v193
	s_add_i32 s4, s25, 1
	s_cmp_le_u32 s4, s24
	s_cselect_b64 s[76:77], -1, 0
	s_cmp_gt_u32 s4, s24
	s_cbranch_scc1 .LBB0_1137
	v_add_u32_e32 v84, 0x4000, v255
	v_add_u32_e32 v85, 0x6000, v255
	global_load_dwordx4 v[162:165], v84, s[42:43]
	global_load_dwordx4 v[166:169], v85, s[42:43]
	global_load_dwordx4 v[170:173], v84, s[22:23]
	global_load_dwordx4 v[174:177], v85, s[22:23]
